# residual epilogue: per-row sum-of-squares reduction across the four 16-lane groups via v_permlane16_swap/v_permlane32_swap instead of two ds_bpermute round trips
# speedup vs baseline: 1.0072x; 1.0029x over previous
.LBB0_858:
	v_lshl_add_u32 v140, s51, 8, v144
	v_ashrrev_i32_e32 v141, 31, v140
	v_lshl_or_b32 v138, s36, 8, v146
	v_lshlrev_b64 v[142:143], 11, v[140:141]
	v_ashrrev_i32_e32 v139, 31, v138
	v_lshl_add_u64 v[142:143], s[80:81], 0, v[142:143]
	v_lshl_add_u64 v[142:143], v[138:139], 1, v[142:143]
	global_load_dwordx4 v[148:151], v[142:143], off
	global_load_dwordx4 v[156:159], v[142:143], off offset:256
	s_mov_b64 s[52:53], 0x8000
	v_lshl_add_u64 v[226:227], s[52:53], 0, v[142:143]
	global_load_dwordx4 v[160:163], v[226:227], off
	global_load_dwordx4 v[164:167], v[226:227], off offset:256
	s_mov_b64 s[52:53], 0x10000
	v_lshl_add_u64 v[226:227], s[52:53], 0, v[142:143]
	global_load_dwordx4 v[168:171], v[226:227], off
	global_load_dwordx4 v[172:175], v[226:227], off offset:256
	s_mov_b64 s[52:53], 0x18000
	v_lshl_add_u64 v[226:227], s[52:53], 0, v[142:143]
	global_load_dwordx4 v[176:179], v[226:227], off
	global_load_dwordx4 v[180:183], v[226:227], off offset:256
	s_mov_b64 s[52:53], 0x40000
	v_lshl_add_u64 v[226:227], s[52:53], 0, v[142:143]
	global_load_dwordx4 v[184:187], v[226:227], off
	global_load_dwordx4 v[188:191], v[226:227], off offset:256
	s_mov_b64 s[52:53], 0x48000
	v_lshl_add_u64 v[226:227], s[52:53], 0, v[142:143]
	global_load_dwordx4 v[192:195], v[226:227], off
	global_load_dwordx4 v[204:207], v[226:227], off offset:256
	s_mov_b64 s[52:53], 0x50000
	v_lshl_add_u64 v[226:227], s[52:53], 0, v[142:143]
	global_load_dwordx4 v[208:211], v[226:227], off
	global_load_dwordx4 v[212:215], v[226:227], off offset:256
	s_mov_b64 s[52:53], 0x58000
	v_lshl_add_u64 v[226:227], s[52:53], 0, v[142:143]
	global_load_dwordx4 v[216:219], v[226:227], off
	global_load_dwordx4 v[228:231], v[226:227], off offset:256
	s_lshl_b32 s34, s36, 2
	s_ashr_i32 s35, s34, 31
	s_waitcnt vmcnt(15)
	v_lshlrev_b32_e32 v152, 16, v148
	v_fmac_f32_e32 v152, s2, v124
	v_and_b32_e32 v124, 0xffff0000, v148
	v_fmac_f32_e32 v124, s2, v125
	v_cvt_pk_bf16_f32 v124, v152, v124
	s_nop 0
	v_and_b32_e32 v148, 0xffff0000, v124
	v_lshlrev_b32_e32 v125, 16, v124
	v_mul_f32_e32 v148, v148, v148
	v_fmac_f32_e32 v148, v125, v125
	v_lshlrev_b32_e32 v125, 16, v149
	v_fmac_f32_e32 v125, s2, v126
	v_and_b32_e32 v126, 0xffff0000, v149
	v_fmac_f32_e32 v126, s2, v127
	v_cvt_pk_bf16_f32 v125, v125, v126
	s_nop 0
	v_and_b32_e32 v127, 0xffff0000, v125
	v_lshlrev_b32_e32 v126, 16, v125
	v_mul_f32_e32 v127, v127, v127
	v_fmac_f32_e32 v127, v126, v126
	v_lshlrev_b32_e32 v126, 16, v150
	v_fmac_f32_e32 v126, s2, v120
	v_and_b32_e32 v120, 0xffff0000, v150
	v_fmac_f32_e32 v120, s2, v121
	v_cvt_pk_bf16_f32 v126, v126, v120
	v_add_f32_e32 v127, v148, v127
	v_and_b32_e32 v121, 0xffff0000, v126
	v_lshlrev_b32_e32 v120, 16, v126
	v_mul_f32_e32 v121, v121, v121
	v_fmac_f32_e32 v121, v120, v120
	v_add_f32_e32 v120, v127, v121
	v_lshlrev_b32_e32 v121, 16, v151
	v_fmac_f32_e32 v121, s2, v122
	v_and_b32_e32 v122, 0xffff0000, v151
	v_fmac_f32_e32 v122, s2, v123
	v_cvt_pk_bf16_f32 v127, v121, v122
	global_store_dwordx4 v[142:143], v[124:127], off
	v_and_b32_e32 v122, 0xffff0000, v127
	v_lshlrev_b32_e32 v121, 16, v127
	v_mul_f32_e32 v122, v122, v122
	v_fmac_f32_e32 v122, v121, v121
	v_add_f32_e32 v148, v120, v122
	s_waitcnt vmcnt(15)
	v_mov_b64_e32 v[120:121], v[156:157]
	v_mov_b64_e32 v[122:123], v[158:159]
	v_lshlrev_b32_e32 v124, 16, v120
	v_fmac_f32_e32 v124, s2, v116
	v_and_b32_e32 v116, 0xffff0000, v120
	v_fmac_f32_e32 v116, s2, v117
	v_cvt_pk_bf16_f32 v116, v124, v116
	s_nop 0
	v_and_b32_e32 v120, 0xffff0000, v116
	v_lshlrev_b32_e32 v117, 16, v116
	v_mul_f32_e32 v120, v120, v120
	v_fmac_f32_e32 v120, v117, v117
	v_lshlrev_b32_e32 v117, 16, v121
	v_fmac_f32_e32 v117, s2, v118
	v_and_b32_e32 v118, 0xffff0000, v121
	v_fmac_f32_e32 v118, s2, v119
	v_cvt_pk_bf16_f32 v117, v117, v118
	v_add_f32_e32 v120, v148, v120
	v_and_b32_e32 v119, 0xffff0000, v117
	v_lshlrev_b32_e32 v118, 16, v117
	v_mul_f32_e32 v119, v119, v119
	v_fmac_f32_e32 v119, v118, v118
	v_lshlrev_b32_e32 v118, 16, v122
	v_fmac_f32_e32 v118, s2, v112
	v_and_b32_e32 v112, 0xffff0000, v122
	v_fmac_f32_e32 v112, s2, v113
	v_cvt_pk_bf16_f32 v118, v118, v112
	v_add_f32_e32 v119, v120, v119
	v_and_b32_e32 v113, 0xffff0000, v118
	v_lshlrev_b32_e32 v112, 16, v118
	v_mul_f32_e32 v113, v113, v113
	v_fmac_f32_e32 v113, v112, v112
	v_add_f32_e32 v112, v119, v113
	v_lshlrev_b32_e32 v113, 16, v123
	v_fmac_f32_e32 v113, s2, v114
	v_and_b32_e32 v114, 0xffff0000, v123
	v_fmac_f32_e32 v114, s2, v115
	v_cvt_pk_bf16_f32 v119, v113, v114
	global_store_dwordx4 v[142:143], v[116:119], off offset:256
	v_and_b32_e32 v114, 0xffff0000, v119
	v_lshlrev_b32_e32 v113, 16, v119
	v_mul_f32_e32 v114, v114, v114
	v_fmac_f32_e32 v114, v113, v113
	v_add_f32_e32 v112, v112, v114
	v_and_b32_e32 v114, 64, v222
	v_xor_b32_e32 v113, 16, v222
	v_add_u32_e32 v115, 64, v114
	v_cmp_lt_i32_e32 vcc, v113, v115
	s_nop 1
	v_cndmask_b32_e32 v113, v222, v113, vcc
	v_lshlrev_b32_e32 v114, 2, v113
	v_mov_b32_e32 v113, v112
	s_nop 1
	v_permlane16_swap_b32_e32 v112, v113
	s_waitcnt lgkmcnt(0)
	v_add_f32_e32 v112, v112, v113
	v_xor_b32_e32 v113, 32, v222
	v_cmp_lt_i32_e32 vcc, v113, v115
	s_nop 1
	v_cndmask_b32_e32 v113, v222, v113, vcc
	v_lshlrev_b32_e32 v115, 2, v113
	v_mov_b32_e32 v113, v112
	s_nop 1
	v_permlane32_swap_b32_e32 v112, v113
	s_and_saveexec_b64 s[44:45], s[40:41]
	s_cbranch_execz .LBB0_860
	v_lshlrev_b64 v[116:117], 6, v[140:141]
	v_lshl_add_u64 v[116:117], s[20:21], 0, v[116:117]
	v_lshl_add_u64 v[116:117], s[34:35], 2, v[116:117]
	s_lshl_b32 s36, s27, 2
	v_lshl_add_u64 v[116:117], v[116:117], 0, s[36:37]
	s_waitcnt lgkmcnt(0)
	v_add_f32_e32 v112, v112, v113
	global_store_dword v[116:117], v112, off
.LBB0_860:
	s_or_b64 exec, exec, s[44:45]
	v_or_b32_e32 v112, 16, v140
	s_waitcnt lgkmcnt(0)
	v_ashrrev_i32_e32 v113, 31, v112
	v_lshlrev_b64 v[116:117], 11, v[112:113]
	v_lshl_add_u64 v[116:117], s[80:81], 0, v[116:117]
	v_lshl_add_u64 v[120:121], v[138:139], 1, v[116:117]
	s_waitcnt vmcnt(16)
	v_mov_b64_e32 v[116:117], v[160:161]
	v_mov_b64_e32 v[118:119], v[162:163]
	v_lshlrev_b32_e32 v122, 16, v116
	v_and_b32_e32 v116, 0xffff0000, v116
	v_lshlrev_b32_e32 v123, 16, v117
	v_and_b32_e32 v117, 0xffff0000, v117
	v_lshlrev_b32_e32 v124, 16, v118
	v_and_b32_e32 v118, 0xffff0000, v118
	v_lshlrev_b32_e32 v125, 16, v119
	v_and_b32_e32 v119, 0xffff0000, v119
	v_fmac_f32_e32 v122, s2, v108
	v_fmac_f32_e32 v116, s2, v109
	v_fmac_f32_e32 v123, s2, v110
	v_fmac_f32_e32 v117, s2, v111
	v_fmac_f32_e32 v124, s2, v104
	v_fmac_f32_e32 v118, s2, v105
	v_fmac_f32_e32 v125, s2, v106
	v_fmac_f32_e32 v119, s2, v107
	v_cvt_pk_bf16_f32 v104, v122, v116
	v_cvt_pk_bf16_f32 v105, v123, v117
	v_cvt_pk_bf16_f32 v106, v124, v118
	v_cvt_pk_bf16_f32 v107, v125, v119
	v_and_b32_e32 v117, 0xffff0000, v104
	v_and_b32_e32 v119, 0xffff0000, v105
	v_lshlrev_b32_e32 v116, 16, v104
	v_lshlrev_b32_e32 v118, 16, v105
	v_and_b32_e32 v123, 0xffff0000, v106
	global_store_dwordx4 v[120:121], v[104:107], off
	v_lshlrev_b32_e32 v122, 16, v106
	v_and_b32_e32 v125, 0xffff0000, v107
	v_mul_f32_e32 v104, v117, v117
	v_mul_f32_e32 v105, v119, v119
	v_mul_f32_e32 v106, v123, v123
	v_fmac_f32_e32 v104, v116, v116
	v_fmac_f32_e32 v105, v118, v118
	v_lshlrev_b32_e32 v124, 16, v107
	v_mul_f32_e32 v107, v125, v125
	v_fmac_f32_e32 v106, v122, v122
	v_add_f32_e32 v104, v104, v105
	v_fmac_f32_e32 v107, v124, v124
	v_add_f32_e32 v104, v104, v106
	v_add_f32_e32 v104, v104, v107
	s_waitcnt vmcnt(16)
	v_mov_b64_e32 v[108:109], v[164:165]
	v_mov_b64_e32 v[110:111], v[166:167]
	v_lshlrev_b32_e32 v105, 16, v108
	v_and_b32_e32 v106, 0xffff0000, v108
	v_lshlrev_b32_e32 v107, 16, v109
	v_and_b32_e32 v108, 0xffff0000, v109
	v_lshlrev_b32_e32 v109, 16, v110
	v_and_b32_e32 v110, 0xffff0000, v110
	v_lshlrev_b32_e32 v116, 16, v111
	v_and_b32_e32 v111, 0xffff0000, v111
	v_fmac_f32_e32 v105, s2, v100
	v_fmac_f32_e32 v106, s2, v101
	v_fmac_f32_e32 v110, s2, v97
	v_fmac_f32_e32 v116, s2, v98
	v_cvt_pk_bf16_f32 v98, v105, v106
	v_fmac_f32_e32 v107, s2, v102
	v_and_b32_e32 v97, 0xffff0000, v98
	v_fmac_f32_e32 v108, s2, v103
	v_fmac_f32_e32 v109, s2, v96
	v_fmac_f32_e32 v111, s2, v99
	v_cvt_pk_bf16_f32 v99, v107, v108
	v_lshlrev_b32_e32 v96, 16, v98
	v_and_b32_e32 v103, 0xffff0000, v99
	v_mul_f32_e32 v97, v97, v97
	v_cvt_pk_bf16_f32 v100, v109, v110
	v_lshlrev_b32_e32 v102, 16, v99
	v_and_b32_e32 v106, 0xffff0000, v100
	v_mul_f32_e32 v103, v103, v103
	v_fmac_f32_e32 v97, v96, v96
	v_cvt_pk_bf16_f32 v101, v116, v111
	v_lshlrev_b32_e32 v105, 16, v100
	v_and_b32_e32 v108, 0xffff0000, v101
	v_mul_f32_e32 v106, v106, v106
	v_fmac_f32_e32 v103, v102, v102
	v_add_f32_e32 v96, v104, v97
	v_lshlrev_b32_e32 v107, 16, v101
	v_mul_f32_e32 v108, v108, v108
	v_fmac_f32_e32 v106, v105, v105
	v_add_f32_e32 v96, v96, v103
	v_add_f32_e32 v96, v96, v106
	v_fmac_f32_e32 v108, v107, v107
	v_add_f32_e32 v96, v96, v108
	v_mov_b32_e32 v97, v96
	s_nop 1
	v_permlane16_swap_b32_e32 v96, v97
	global_store_dwordx4 v[120:121], v[98:101], off offset:256
	s_waitcnt lgkmcnt(0)
	v_add_f32_e32 v96, v96, v97
	v_mov_b32_e32 v97, v96
	s_nop 1
	v_permlane32_swap_b32_e32 v96, v97
	s_and_saveexec_b64 s[44:45], s[40:41]
	s_cbranch_execz .LBB0_862
	v_lshlrev_b64 v[98:99], 6, v[112:113]
	v_lshl_add_u64 v[98:99], s[20:21], 0, v[98:99]
	v_lshl_add_u64 v[98:99], s[34:35], 2, v[98:99]
	s_lshl_b32 s36, s27, 2
	v_lshl_add_u64 v[98:99], v[98:99], 0, s[36:37]
	s_waitcnt lgkmcnt(0)
	v_add_f32_e32 v96, v96, v97
	global_store_dword v[98:99], v96, off
.LBB0_862:
	s_or_b64 exec, exec, s[44:45]
	v_or_b32_e32 v96, 32, v140
	s_waitcnt lgkmcnt(0)
	v_ashrrev_i32_e32 v97, 31, v96
	v_lshlrev_b64 v[98:99], 11, v[96:97]
	v_lshl_add_u64 v[98:99], s[80:81], 0, v[98:99]
	v_lshl_add_u64 v[102:103], v[138:139], 1, v[98:99]
	s_waitcnt vmcnt(17)
	v_mov_b64_e32 v[98:99], v[168:169]
	v_mov_b64_e32 v[100:101], v[170:171]
	v_lshlrev_b32_e32 v104, 16, v98
	v_and_b32_e32 v98, 0xffff0000, v98
	v_lshlrev_b32_e32 v105, 16, v99
	v_and_b32_e32 v99, 0xffff0000, v99
	v_lshlrev_b32_e32 v106, 16, v100
	v_and_b32_e32 v100, 0xffff0000, v100
	v_lshlrev_b32_e32 v107, 16, v101
	v_and_b32_e32 v101, 0xffff0000, v101
	v_fmac_f32_e32 v104, s2, v92
	v_fmac_f32_e32 v98, s2, v93
	v_fmac_f32_e32 v105, s2, v94
	v_fmac_f32_e32 v99, s2, v95
	v_fmac_f32_e32 v106, s2, v88
	v_fmac_f32_e32 v100, s2, v89
	v_fmac_f32_e32 v107, s2, v90
	v_fmac_f32_e32 v101, s2, v91
	v_cvt_pk_bf16_f32 v88, v104, v98
	v_cvt_pk_bf16_f32 v89, v105, v99
	v_cvt_pk_bf16_f32 v90, v106, v100
	v_cvt_pk_bf16_f32 v91, v107, v101
	v_and_b32_e32 v99, 0xffff0000, v88
	v_and_b32_e32 v101, 0xffff0000, v89
	v_lshlrev_b32_e32 v98, 16, v88
	v_lshlrev_b32_e32 v100, 16, v89
	v_and_b32_e32 v105, 0xffff0000, v90
	global_store_dwordx4 v[102:103], v[88:91], off
	v_lshlrev_b32_e32 v104, 16, v90
	v_and_b32_e32 v107, 0xffff0000, v91
	v_mul_f32_e32 v88, v99, v99
	v_mul_f32_e32 v89, v101, v101
	v_mul_f32_e32 v90, v105, v105
	v_fmac_f32_e32 v88, v98, v98
	v_fmac_f32_e32 v89, v100, v100
	v_lshlrev_b32_e32 v106, 16, v91
	v_mul_f32_e32 v91, v107, v107
	v_fmac_f32_e32 v90, v104, v104
	v_add_f32_e32 v88, v88, v89
	v_fmac_f32_e32 v91, v106, v106
	v_add_f32_e32 v88, v88, v90
	v_add_f32_e32 v88, v88, v91
	s_waitcnt vmcnt(17)
	v_mov_b64_e32 v[92:93], v[172:173]
	v_mov_b64_e32 v[94:95], v[174:175]
	v_lshlrev_b32_e32 v89, 16, v92
	v_and_b32_e32 v90, 0xffff0000, v92
	v_lshlrev_b32_e32 v91, 16, v93
	v_and_b32_e32 v92, 0xffff0000, v93
	v_lshlrev_b32_e32 v93, 16, v94
	v_and_b32_e32 v94, 0xffff0000, v94
	v_lshlrev_b32_e32 v98, 16, v95
	v_and_b32_e32 v95, 0xffff0000, v95
	v_fmac_f32_e32 v89, s2, v84
	v_fmac_f32_e32 v90, s2, v85
	v_fmac_f32_e32 v94, s2, v81
	v_fmac_f32_e32 v98, s2, v82
	v_cvt_pk_bf16_f32 v82, v89, v90
	v_fmac_f32_e32 v91, s2, v86
	v_and_b32_e32 v81, 0xffff0000, v82
	v_fmac_f32_e32 v92, s2, v87
	v_fmac_f32_e32 v93, s2, v80
	v_fmac_f32_e32 v95, s2, v83
	v_cvt_pk_bf16_f32 v83, v91, v92
	v_lshlrev_b32_e32 v80, 16, v82
	v_and_b32_e32 v87, 0xffff0000, v83
	v_mul_f32_e32 v81, v81, v81
	v_cvt_pk_bf16_f32 v84, v93, v94
	v_lshlrev_b32_e32 v86, 16, v83
	v_and_b32_e32 v90, 0xffff0000, v84
	v_mul_f32_e32 v87, v87, v87
	v_fmac_f32_e32 v81, v80, v80
	v_cvt_pk_bf16_f32 v85, v98, v95
	v_lshlrev_b32_e32 v89, 16, v84
	v_and_b32_e32 v92, 0xffff0000, v85
	v_mul_f32_e32 v90, v90, v90
	v_fmac_f32_e32 v87, v86, v86
	v_add_f32_e32 v80, v88, v81
	v_lshlrev_b32_e32 v91, 16, v85
	v_mul_f32_e32 v92, v92, v92
	v_fmac_f32_e32 v90, v89, v89
	v_add_f32_e32 v80, v80, v87
	v_add_f32_e32 v80, v80, v90
	v_fmac_f32_e32 v92, v91, v91
	v_add_f32_e32 v80, v80, v92
	v_mov_b32_e32 v81, v80
	s_nop 1
	v_permlane16_swap_b32_e32 v80, v81
	global_store_dwordx4 v[102:103], v[82:85], off offset:256
	s_waitcnt lgkmcnt(0)
	v_add_f32_e32 v80, v80, v81
	v_mov_b32_e32 v81, v80
	s_nop 1
	v_permlane32_swap_b32_e32 v80, v81
	s_and_saveexec_b64 s[44:45], s[40:41]
	s_cbranch_execz .LBB0_864
	v_lshlrev_b64 v[82:83], 6, v[96:97]
	v_lshl_add_u64 v[82:83], s[20:21], 0, v[82:83]
	v_lshl_add_u64 v[82:83], s[34:35], 2, v[82:83]
	s_lshl_b32 s36, s27, 2
	v_lshl_add_u64 v[82:83], v[82:83], 0, s[36:37]
	s_waitcnt lgkmcnt(0)
	v_add_f32_e32 v80, v80, v81
	global_store_dword v[82:83], v80, off
.LBB0_864:
	s_or_b64 exec, exec, s[44:45]
	v_or_b32_e32 v80, 48, v140
	s_waitcnt lgkmcnt(0)
	v_ashrrev_i32_e32 v81, 31, v80
	v_lshlrev_b64 v[82:83], 11, v[80:81]
	v_lshl_add_u64 v[82:83], s[80:81], 0, v[82:83]
	v_lshl_add_u64 v[86:87], v[138:139], 1, v[82:83]
	s_waitcnt vmcnt(18)
	v_mov_b64_e32 v[82:83], v[176:177]
	v_mov_b64_e32 v[84:85], v[178:179]
	v_lshlrev_b32_e32 v88, 16, v82
	v_and_b32_e32 v82, 0xffff0000, v82
	v_lshlrev_b32_e32 v89, 16, v83
	v_and_b32_e32 v83, 0xffff0000, v83
	v_lshlrev_b32_e32 v90, 16, v84
	v_and_b32_e32 v84, 0xffff0000, v84
	v_lshlrev_b32_e32 v91, 16, v85
	v_and_b32_e32 v85, 0xffff0000, v85
	v_fmac_f32_e32 v88, s2, v76
	v_fmac_f32_e32 v82, s2, v77
	v_fmac_f32_e32 v89, s2, v78
	v_fmac_f32_e32 v83, s2, v79
	v_fmac_f32_e32 v90, s2, v72
	v_fmac_f32_e32 v84, s2, v73
	v_fmac_f32_e32 v91, s2, v74
	v_fmac_f32_e32 v85, s2, v75
	v_cvt_pk_bf16_f32 v72, v88, v82
	v_cvt_pk_bf16_f32 v73, v89, v83
	v_cvt_pk_bf16_f32 v74, v90, v84
	v_cvt_pk_bf16_f32 v75, v91, v85
	v_and_b32_e32 v83, 0xffff0000, v72
	v_and_b32_e32 v85, 0xffff0000, v73
	v_lshlrev_b32_e32 v82, 16, v72
	v_lshlrev_b32_e32 v84, 16, v73
	v_and_b32_e32 v89, 0xffff0000, v74
	global_store_dwordx4 v[86:87], v[72:75], off
	v_lshlrev_b32_e32 v88, 16, v74
	v_and_b32_e32 v91, 0xffff0000, v75
	v_mul_f32_e32 v72, v83, v83
	v_mul_f32_e32 v73, v85, v85
	v_mul_f32_e32 v74, v89, v89
	v_fmac_f32_e32 v72, v82, v82
	v_fmac_f32_e32 v73, v84, v84
	v_lshlrev_b32_e32 v90, 16, v75
	v_mul_f32_e32 v75, v91, v91
	v_fmac_f32_e32 v74, v88, v88
	v_add_f32_e32 v72, v72, v73
	v_fmac_f32_e32 v75, v90, v90
	v_add_f32_e32 v72, v72, v74
	v_add_f32_e32 v72, v72, v75
	s_waitcnt vmcnt(18)
	v_mov_b64_e32 v[76:77], v[180:181]
	v_mov_b64_e32 v[78:79], v[182:183]
	v_lshlrev_b32_e32 v73, 16, v76
	v_and_b32_e32 v74, 0xffff0000, v76
	v_lshlrev_b32_e32 v75, 16, v77
	v_and_b32_e32 v76, 0xffff0000, v77
	v_lshlrev_b32_e32 v77, 16, v78
	v_and_b32_e32 v78, 0xffff0000, v78
	v_lshlrev_b32_e32 v82, 16, v79
	v_and_b32_e32 v79, 0xffff0000, v79
	v_fmac_f32_e32 v73, s2, v68
	v_fmac_f32_e32 v74, s2, v69
	v_fmac_f32_e32 v78, s2, v65
	v_fmac_f32_e32 v82, s2, v66
	v_cvt_pk_bf16_f32 v66, v73, v74
	v_fmac_f32_e32 v75, s2, v70
	v_and_b32_e32 v65, 0xffff0000, v66
	v_fmac_f32_e32 v76, s2, v71
	v_fmac_f32_e32 v77, s2, v64
	v_fmac_f32_e32 v79, s2, v67
	v_cvt_pk_bf16_f32 v67, v75, v76
	v_lshlrev_b32_e32 v64, 16, v66
	v_and_b32_e32 v71, 0xffff0000, v67
	v_mul_f32_e32 v65, v65, v65
	v_cvt_pk_bf16_f32 v68, v77, v78
	v_lshlrev_b32_e32 v70, 16, v67
	v_and_b32_e32 v74, 0xffff0000, v68
	v_mul_f32_e32 v71, v71, v71
	v_fmac_f32_e32 v65, v64, v64
	v_cvt_pk_bf16_f32 v69, v82, v79
	v_lshlrev_b32_e32 v73, 16, v68
	v_and_b32_e32 v76, 0xffff0000, v69
	v_mul_f32_e32 v74, v74, v74
	v_fmac_f32_e32 v71, v70, v70
	v_add_f32_e32 v64, v72, v65
	v_lshlrev_b32_e32 v75, 16, v69
	v_mul_f32_e32 v76, v76, v76
	v_fmac_f32_e32 v74, v73, v73
	v_add_f32_e32 v64, v64, v71
	v_add_f32_e32 v64, v64, v74
	v_fmac_f32_e32 v76, v75, v75
	v_add_f32_e32 v64, v64, v76
	v_mov_b32_e32 v65, v64
	s_nop 1
	v_permlane16_swap_b32_e32 v64, v65
	global_store_dwordx4 v[86:87], v[66:69], off offset:256
	s_waitcnt lgkmcnt(0)
	v_add_f32_e32 v64, v64, v65
	v_mov_b32_e32 v65, v64
	s_nop 1
	v_permlane32_swap_b32_e32 v64, v65
	s_and_saveexec_b64 s[44:45], s[40:41]
	s_cbranch_execz .LBB0_866
	v_lshlrev_b64 v[66:67], 6, v[80:81]
	v_lshl_add_u64 v[66:67], s[20:21], 0, v[66:67]
	v_lshl_add_u64 v[66:67], s[34:35], 2, v[66:67]
	s_lshl_b32 s36, s27, 2
	v_lshl_add_u64 v[66:67], v[66:67], 0, s[36:37]
	s_waitcnt lgkmcnt(0)
	v_add_f32_e32 v64, v64, v65
	global_store_dword v[66:67], v64, off
.LBB0_866:
	s_or_b64 exec, exec, s[44:45]
	v_add_u32_e32 v64, 0x80, v140
	s_waitcnt lgkmcnt(0)
	v_ashrrev_i32_e32 v65, 31, v64
	v_lshlrev_b64 v[66:67], 11, v[64:65]
	v_lshl_add_u64 v[66:67], s[80:81], 0, v[66:67]
	v_lshl_add_u64 v[70:71], v[138:139], 1, v[66:67]
	s_waitcnt vmcnt(19)
	v_mov_b64_e32 v[66:67], v[184:185]
	v_mov_b64_e32 v[68:69], v[186:187]
	v_lshlrev_b32_e32 v72, 16, v66
	v_and_b32_e32 v66, 0xffff0000, v66
	v_lshlrev_b32_e32 v73, 16, v67
	v_and_b32_e32 v67, 0xffff0000, v67
	v_lshlrev_b32_e32 v74, 16, v68
	v_and_b32_e32 v68, 0xffff0000, v68
	v_lshlrev_b32_e32 v75, 16, v69
	v_and_b32_e32 v69, 0xffff0000, v69
	v_fmac_f32_e32 v72, s2, v60
	v_fmac_f32_e32 v66, s2, v61
	v_fmac_f32_e32 v73, s2, v62
	v_fmac_f32_e32 v67, s2, v63
	v_fmac_f32_e32 v74, s2, v56
	v_fmac_f32_e32 v68, s2, v57
	v_fmac_f32_e32 v75, s2, v58
	v_fmac_f32_e32 v69, s2, v59
	v_cvt_pk_bf16_f32 v56, v72, v66
	v_cvt_pk_bf16_f32 v57, v73, v67
	v_cvt_pk_bf16_f32 v58, v74, v68
	v_cvt_pk_bf16_f32 v59, v75, v69
	v_and_b32_e32 v67, 0xffff0000, v56
	v_and_b32_e32 v69, 0xffff0000, v57
	v_lshlrev_b32_e32 v66, 16, v56
	v_lshlrev_b32_e32 v68, 16, v57
	v_and_b32_e32 v73, 0xffff0000, v58
	global_store_dwordx4 v[70:71], v[56:59], off
	v_lshlrev_b32_e32 v72, 16, v58
	v_and_b32_e32 v75, 0xffff0000, v59
	v_mul_f32_e32 v56, v67, v67
	v_mul_f32_e32 v57, v69, v69
	v_mul_f32_e32 v58, v73, v73
	v_fmac_f32_e32 v56, v66, v66
	v_fmac_f32_e32 v57, v68, v68
	v_lshlrev_b32_e32 v74, 16, v59
	v_mul_f32_e32 v59, v75, v75
	v_fmac_f32_e32 v58, v72, v72
	v_add_f32_e32 v56, v56, v57
	v_fmac_f32_e32 v59, v74, v74
	v_add_f32_e32 v56, v56, v58
	v_add_f32_e32 v56, v56, v59
	s_waitcnt vmcnt(19)
	v_mov_b64_e32 v[60:61], v[188:189]
	v_mov_b64_e32 v[62:63], v[190:191]
	v_lshlrev_b32_e32 v57, 16, v60
	v_and_b32_e32 v58, 0xffff0000, v60
	v_lshlrev_b32_e32 v59, 16, v61
	v_and_b32_e32 v60, 0xffff0000, v61
	v_lshlrev_b32_e32 v61, 16, v62
	v_and_b32_e32 v62, 0xffff0000, v62
	v_lshlrev_b32_e32 v66, 16, v63
	v_and_b32_e32 v63, 0xffff0000, v63
	v_fmac_f32_e32 v57, s2, v52
	v_fmac_f32_e32 v58, s2, v53
	v_fmac_f32_e32 v62, s2, v49
	v_fmac_f32_e32 v66, s2, v50
	v_cvt_pk_bf16_f32 v50, v57, v58
	v_fmac_f32_e32 v59, s2, v54
	v_and_b32_e32 v49, 0xffff0000, v50
	v_fmac_f32_e32 v60, s2, v55
	v_fmac_f32_e32 v61, s2, v48
	v_fmac_f32_e32 v63, s2, v51
	v_cvt_pk_bf16_f32 v51, v59, v60
	v_lshlrev_b32_e32 v48, 16, v50
	v_and_b32_e32 v55, 0xffff0000, v51
	v_mul_f32_e32 v49, v49, v49
	v_cvt_pk_bf16_f32 v52, v61, v62
	v_lshlrev_b32_e32 v54, 16, v51
	v_and_b32_e32 v58, 0xffff0000, v52
	v_mul_f32_e32 v55, v55, v55
	v_fmac_f32_e32 v49, v48, v48
	v_cvt_pk_bf16_f32 v53, v66, v63
	v_lshlrev_b32_e32 v57, 16, v52
	v_and_b32_e32 v60, 0xffff0000, v53
	v_mul_f32_e32 v58, v58, v58
	v_fmac_f32_e32 v55, v54, v54
	v_add_f32_e32 v48, v56, v49
	v_lshlrev_b32_e32 v59, 16, v53
	v_mul_f32_e32 v60, v60, v60
	v_fmac_f32_e32 v58, v57, v57
	v_add_f32_e32 v48, v48, v55
	v_add_f32_e32 v48, v48, v58
	v_fmac_f32_e32 v60, v59, v59
	v_add_f32_e32 v48, v48, v60
	v_mov_b32_e32 v49, v48
	s_nop 1
	v_permlane16_swap_b32_e32 v48, v49
	global_store_dwordx4 v[70:71], v[50:53], off offset:256
	s_waitcnt lgkmcnt(0)
	v_add_f32_e32 v48, v48, v49
	v_mov_b32_e32 v49, v48
	s_nop 1
	v_permlane32_swap_b32_e32 v48, v49
	s_and_saveexec_b64 s[44:45], s[40:41]
	s_cbranch_execz .LBB0_868
	v_lshlrev_b64 v[50:51], 6, v[64:65]
	v_lshl_add_u64 v[50:51], s[20:21], 0, v[50:51]
	v_lshl_add_u64 v[50:51], s[34:35], 2, v[50:51]
	s_lshl_b32 s36, s27, 2
	v_lshl_add_u64 v[50:51], v[50:51], 0, s[36:37]
	s_waitcnt lgkmcnt(0)
	v_add_f32_e32 v48, v48, v49
	global_store_dword v[50:51], v48, off
.LBB0_868:
	s_or_b64 exec, exec, s[44:45]
	v_add_u32_e32 v48, 0x90, v140
	s_waitcnt lgkmcnt(0)
	v_ashrrev_i32_e32 v49, 31, v48
	v_lshlrev_b64 v[50:51], 11, v[48:49]
	v_lshl_add_u64 v[50:51], s[80:81], 0, v[50:51]
	v_lshl_add_u64 v[54:55], v[138:139], 1, v[50:51]
	s_waitcnt vmcnt(20)
	v_mov_b64_e32 v[50:51], v[192:193]
	v_mov_b64_e32 v[52:53], v[194:195]
	v_lshlrev_b32_e32 v56, 16, v50
	v_and_b32_e32 v50, 0xffff0000, v50
	v_lshlrev_b32_e32 v57, 16, v51
	v_and_b32_e32 v51, 0xffff0000, v51
	v_lshlrev_b32_e32 v58, 16, v52
	v_and_b32_e32 v52, 0xffff0000, v52
	v_lshlrev_b32_e32 v59, 16, v53
	v_and_b32_e32 v53, 0xffff0000, v53
	v_fmac_f32_e32 v56, s2, v44
	v_fmac_f32_e32 v50, s2, v45
	v_fmac_f32_e32 v57, s2, v46
	v_fmac_f32_e32 v51, s2, v47
	v_fmac_f32_e32 v58, s2, v40
	v_fmac_f32_e32 v52, s2, v41
	v_fmac_f32_e32 v59, s2, v42
	v_fmac_f32_e32 v53, s2, v43
	v_cvt_pk_bf16_f32 v40, v56, v50
	v_cvt_pk_bf16_f32 v41, v57, v51
	v_cvt_pk_bf16_f32 v42, v58, v52
	v_cvt_pk_bf16_f32 v43, v59, v53
	v_and_b32_e32 v51, 0xffff0000, v40
	v_and_b32_e32 v53, 0xffff0000, v41
	v_lshlrev_b32_e32 v50, 16, v40
	v_lshlrev_b32_e32 v52, 16, v41
	v_and_b32_e32 v57, 0xffff0000, v42
	global_store_dwordx4 v[54:55], v[40:43], off
	v_lshlrev_b32_e32 v56, 16, v42
	v_and_b32_e32 v59, 0xffff0000, v43
	v_mul_f32_e32 v40, v51, v51
	v_mul_f32_e32 v41, v53, v53
	v_mul_f32_e32 v42, v57, v57
	v_fmac_f32_e32 v40, v50, v50
	v_fmac_f32_e32 v41, v52, v52
	v_lshlrev_b32_e32 v58, 16, v43
	v_mul_f32_e32 v43, v59, v59
	v_fmac_f32_e32 v42, v56, v56
	v_add_f32_e32 v40, v40, v41
	v_fmac_f32_e32 v43, v58, v58
	v_add_f32_e32 v40, v40, v42
	v_add_f32_e32 v40, v40, v43
	s_waitcnt vmcnt(20)
	v_mov_b64_e32 v[44:45], v[204:205]
	v_mov_b64_e32 v[46:47], v[206:207]
	v_lshlrev_b32_e32 v41, 16, v44
	v_and_b32_e32 v42, 0xffff0000, v44
	v_lshlrev_b32_e32 v43, 16, v45
	v_and_b32_e32 v44, 0xffff0000, v45
	v_lshlrev_b32_e32 v45, 16, v46
	v_and_b32_e32 v46, 0xffff0000, v46
	v_lshlrev_b32_e32 v50, 16, v47
	v_and_b32_e32 v47, 0xffff0000, v47
	v_fmac_f32_e32 v41, s2, v36
	v_fmac_f32_e32 v42, s2, v37
	v_fmac_f32_e32 v46, s2, v33
	v_fmac_f32_e32 v50, s2, v34
	v_cvt_pk_bf16_f32 v34, v41, v42
	v_fmac_f32_e32 v43, s2, v38
	v_and_b32_e32 v33, 0xffff0000, v34
	v_fmac_f32_e32 v44, s2, v39
	v_fmac_f32_e32 v45, s2, v32
	v_fmac_f32_e32 v47, s2, v35
	v_cvt_pk_bf16_f32 v35, v43, v44
	v_lshlrev_b32_e32 v32, 16, v34
	v_and_b32_e32 v39, 0xffff0000, v35
	v_mul_f32_e32 v33, v33, v33
	v_cvt_pk_bf16_f32 v36, v45, v46
	v_lshlrev_b32_e32 v38, 16, v35
	v_and_b32_e32 v42, 0xffff0000, v36
	v_mul_f32_e32 v39, v39, v39
	v_fmac_f32_e32 v33, v32, v32
	v_cvt_pk_bf16_f32 v37, v50, v47
	v_lshlrev_b32_e32 v41, 16, v36
	v_and_b32_e32 v44, 0xffff0000, v37
	v_mul_f32_e32 v42, v42, v42
	v_fmac_f32_e32 v39, v38, v38
	v_add_f32_e32 v32, v40, v33
	v_lshlrev_b32_e32 v43, 16, v37
	v_mul_f32_e32 v44, v44, v44
	v_fmac_f32_e32 v42, v41, v41
	v_add_f32_e32 v32, v32, v39
	v_add_f32_e32 v32, v32, v42
	v_fmac_f32_e32 v44, v43, v43
	v_add_f32_e32 v32, v32, v44
	v_mov_b32_e32 v33, v32
	s_nop 1
	v_permlane16_swap_b32_e32 v32, v33
	global_store_dwordx4 v[54:55], v[34:37], off offset:256
	s_waitcnt lgkmcnt(0)
	v_add_f32_e32 v32, v32, v33
	v_mov_b32_e32 v33, v32
	s_nop 1
	v_permlane32_swap_b32_e32 v32, v33
	s_and_saveexec_b64 s[44:45], s[40:41]
	s_cbranch_execz .LBB0_870
	v_lshlrev_b64 v[34:35], 6, v[48:49]
	v_lshl_add_u64 v[34:35], s[20:21], 0, v[34:35]
	v_lshl_add_u64 v[34:35], s[34:35], 2, v[34:35]
	s_lshl_b32 s36, s27, 2
	v_lshl_add_u64 v[34:35], v[34:35], 0, s[36:37]
	s_waitcnt lgkmcnt(0)
	v_add_f32_e32 v32, v32, v33
	global_store_dword v[34:35], v32, off
.LBB0_870:
	s_or_b64 exec, exec, s[44:45]
	v_add_u32_e32 v32, 0xa0, v140
	s_waitcnt lgkmcnt(0)
	v_ashrrev_i32_e32 v33, 31, v32
	v_lshlrev_b64 v[34:35], 11, v[32:33]
	v_lshl_add_u64 v[34:35], s[80:81], 0, v[34:35]
	v_lshl_add_u64 v[34:35], v[138:139], 1, v[34:35]
	s_waitcnt vmcnt(21)
	v_mov_b64_e32 v[36:37], v[208:209]
	v_mov_b64_e32 v[38:39], v[210:211]
	v_lshlrev_b32_e32 v40, 16, v36
	v_fmac_f32_e32 v40, s2, v28
	v_and_b32_e32 v28, 0xffff0000, v36
	v_fmac_f32_e32 v28, s2, v29
	v_cvt_pk_bf16_f32 v28, v40, v28
	s_nop 0
	v_and_b32_e32 v36, 0xffff0000, v28
	v_lshlrev_b32_e32 v29, 16, v28
	v_mul_f32_e32 v36, v36, v36
	v_fmac_f32_e32 v36, v29, v29
	v_lshlrev_b32_e32 v29, 16, v37
	v_fmac_f32_e32 v29, s2, v30
	v_and_b32_e32 v30, 0xffff0000, v37
	v_fmac_f32_e32 v30, s2, v31
	v_cvt_pk_bf16_f32 v29, v29, v30
	s_nop 0
	v_and_b32_e32 v31, 0xffff0000, v29
	v_lshlrev_b32_e32 v30, 16, v29
	v_mul_f32_e32 v31, v31, v31
	v_fmac_f32_e32 v31, v30, v30
	v_lshlrev_b32_e32 v30, 16, v38
	v_fmac_f32_e32 v30, s2, v24
	v_and_b32_e32 v24, 0xffff0000, v38
	v_fmac_f32_e32 v24, s2, v25
	v_cvt_pk_bf16_f32 v30, v30, v24
	v_add_f32_e32 v31, v36, v31
	v_and_b32_e32 v25, 0xffff0000, v30
	v_lshlrev_b32_e32 v24, 16, v30
	v_mul_f32_e32 v25, v25, v25
	v_fmac_f32_e32 v25, v24, v24
	v_add_f32_e32 v24, v31, v25
	v_lshlrev_b32_e32 v25, 16, v39
	v_fmac_f32_e32 v25, s2, v26
	v_and_b32_e32 v26, 0xffff0000, v39
	v_fmac_f32_e32 v26, s2, v27
	v_cvt_pk_bf16_f32 v31, v25, v26
	global_store_dwordx4 v[34:35], v[28:31], off
	v_and_b32_e32 v26, 0xffff0000, v31
	v_lshlrev_b32_e32 v25, 16, v31
	v_mul_f32_e32 v26, v26, v26
	v_fmac_f32_e32 v26, v25, v25
	v_add_f32_e32 v36, v24, v26
	s_waitcnt vmcnt(21)
	v_mov_b64_e32 v[24:25], v[212:213]
	v_mov_b64_e32 v[26:27], v[214:215]
	v_lshlrev_b32_e32 v28, 16, v24
	v_fmac_f32_e32 v28, s2, v20
	v_and_b32_e32 v20, 0xffff0000, v24
	v_fmac_f32_e32 v20, s2, v21
	v_cvt_pk_bf16_f32 v20, v28, v20
	s_nop 0
	v_and_b32_e32 v24, 0xffff0000, v20
	v_lshlrev_b32_e32 v21, 16, v20
	v_mul_f32_e32 v24, v24, v24
	v_fmac_f32_e32 v24, v21, v21
	v_lshlrev_b32_e32 v21, 16, v25
	v_fmac_f32_e32 v21, s2, v22
	v_and_b32_e32 v22, 0xffff0000, v25
	v_fmac_f32_e32 v22, s2, v23
	v_cvt_pk_bf16_f32 v21, v21, v22
	v_add_f32_e32 v24, v36, v24
	v_and_b32_e32 v23, 0xffff0000, v21
	v_lshlrev_b32_e32 v22, 16, v21
	v_mul_f32_e32 v23, v23, v23
	v_fmac_f32_e32 v23, v22, v22
	v_lshlrev_b32_e32 v22, 16, v26
	v_fmac_f32_e32 v22, s2, v16
	v_and_b32_e32 v16, 0xffff0000, v26
	v_fmac_f32_e32 v16, s2, v17
	v_cvt_pk_bf16_f32 v22, v22, v16
	v_add_f32_e32 v23, v24, v23
	v_and_b32_e32 v17, 0xffff0000, v22
	v_lshlrev_b32_e32 v16, 16, v22
	v_mul_f32_e32 v17, v17, v17
	v_fmac_f32_e32 v17, v16, v16
	v_add_f32_e32 v16, v23, v17
	v_lshlrev_b32_e32 v17, 16, v27
	v_fmac_f32_e32 v17, s2, v18
	v_and_b32_e32 v18, 0xffff0000, v27
	v_fmac_f32_e32 v18, s2, v19
	v_cvt_pk_bf16_f32 v23, v17, v18
	global_store_dwordx4 v[34:35], v[20:23], off offset:256
	v_and_b32_e32 v18, 0xffff0000, v23
	v_lshlrev_b32_e32 v17, 16, v23
	v_mul_f32_e32 v18, v18, v18
	v_fmac_f32_e32 v18, v17, v17
	v_add_f32_e32 v16, v16, v18
	v_mov_b32_e32 v17, v16
	s_nop 1
	v_permlane16_swap_b32_e32 v16, v17
	s_waitcnt lgkmcnt(0)
	v_add_f32_e32 v16, v16, v17
	v_mov_b32_e32 v17, v16
	s_nop 1
	v_permlane32_swap_b32_e32 v16, v17
	s_and_saveexec_b64 s[44:45], s[40:41]
	s_cbranch_execz .LBB0_872
	v_lshlrev_b64 v[18:19], 6, v[32:33]
	v_lshl_add_u64 v[18:19], s[20:21], 0, v[18:19]
	v_lshl_add_u64 v[18:19], s[34:35], 2, v[18:19]
	s_lshl_b32 s36, s27, 2
	v_lshl_add_u64 v[18:19], v[18:19], 0, s[36:37]
	s_waitcnt lgkmcnt(0)
	v_add_f32_e32 v16, v16, v17
	global_store_dword v[18:19], v16, off
.LBB0_872:
	s_or_b64 exec, exec, s[44:45]
	v_add_u32_e32 v16, 0xb0, v140
	s_waitcnt lgkmcnt(0)
	v_ashrrev_i32_e32 v17, 31, v16
	v_lshlrev_b64 v[18:19], 11, v[16:17]
	v_lshl_add_u64 v[18:19], s[80:81], 0, v[18:19]
	v_lshl_add_u64 v[22:23], v[138:139], 1, v[18:19]
	s_waitcnt vmcnt(22)
	v_mov_b64_e32 v[18:19], v[216:217]
	v_mov_b64_e32 v[20:21], v[218:219]
	v_lshlrev_b32_e32 v24, 16, v18
	v_and_b32_e32 v18, 0xffff0000, v18
	v_lshlrev_b32_e32 v25, 16, v19
	v_and_b32_e32 v19, 0xffff0000, v19
	v_lshlrev_b32_e32 v26, 16, v20
	v_and_b32_e32 v20, 0xffff0000, v20
	v_lshlrev_b32_e32 v27, 16, v21
	v_and_b32_e32 v21, 0xffff0000, v21
	v_fmac_f32_e32 v24, s2, v12
	v_fmac_f32_e32 v18, s2, v13
	v_fmac_f32_e32 v25, s2, v14
	v_fmac_f32_e32 v19, s2, v15
	v_fmac_f32_e32 v26, s2, v8
	v_fmac_f32_e32 v20, s2, v9
	v_fmac_f32_e32 v27, s2, v10
	v_fmac_f32_e32 v21, s2, v11
	v_cvt_pk_bf16_f32 v8, v24, v18
	v_cvt_pk_bf16_f32 v9, v25, v19
	v_cvt_pk_bf16_f32 v10, v26, v20
	v_cvt_pk_bf16_f32 v11, v27, v21
	v_and_b32_e32 v19, 0xffff0000, v8
	v_and_b32_e32 v21, 0xffff0000, v9
	v_lshlrev_b32_e32 v18, 16, v8
	v_lshlrev_b32_e32 v20, 16, v9
	v_and_b32_e32 v25, 0xffff0000, v10
	global_store_dwordx4 v[22:23], v[8:11], off
	v_lshlrev_b32_e32 v24, 16, v10
	v_and_b32_e32 v27, 0xffff0000, v11
	v_mul_f32_e32 v8, v19, v19
	v_mul_f32_e32 v9, v21, v21
	v_mul_f32_e32 v10, v25, v25
	v_fmac_f32_e32 v8, v18, v18
	v_fmac_f32_e32 v9, v20, v20
	v_lshlrev_b32_e32 v26, 16, v11
	v_mul_f32_e32 v11, v27, v27
	v_fmac_f32_e32 v10, v24, v24
	v_add_f32_e32 v8, v8, v9
	v_fmac_f32_e32 v11, v26, v26
	v_add_f32_e32 v8, v8, v10
	v_add_f32_e32 v8, v8, v11
	s_waitcnt vmcnt(22)
	v_mov_b64_e32 v[12:13], v[228:229]
	v_mov_b64_e32 v[14:15], v[230:231]
	v_lshlrev_b32_e32 v9, 16, v12
	v_and_b32_e32 v10, 0xffff0000, v12
	v_lshlrev_b32_e32 v11, 16, v13
	v_and_b32_e32 v12, 0xffff0000, v13
	v_lshlrev_b32_e32 v13, 16, v14
	v_and_b32_e32 v14, 0xffff0000, v14
	v_lshlrev_b32_e32 v18, 16, v15
	v_and_b32_e32 v15, 0xffff0000, v15
	v_fmac_f32_e32 v9, s2, v4
	v_fmac_f32_e32 v10, s2, v5
	v_fmac_f32_e32 v14, s2, v1
	v_fmac_f32_e32 v18, s2, v2
	v_cvt_pk_bf16_f32 v2, v9, v10
	v_fmac_f32_e32 v11, s2, v6
	v_and_b32_e32 v1, 0xffff0000, v2
	v_fmac_f32_e32 v12, s2, v7
	v_fmac_f32_e32 v13, s2, v0
	v_fmac_f32_e32 v15, s2, v3
	v_cvt_pk_bf16_f32 v3, v11, v12
	v_lshlrev_b32_e32 v0, 16, v2
	v_and_b32_e32 v7, 0xffff0000, v3
	v_mul_f32_e32 v1, v1, v1
	v_cvt_pk_bf16_f32 v4, v13, v14
	v_lshlrev_b32_e32 v6, 16, v3
	v_and_b32_e32 v10, 0xffff0000, v4
	v_mul_f32_e32 v7, v7, v7
	v_fmac_f32_e32 v1, v0, v0
	v_cvt_pk_bf16_f32 v5, v18, v15
	v_lshlrev_b32_e32 v9, 16, v4
	v_and_b32_e32 v12, 0xffff0000, v5
	v_mul_f32_e32 v10, v10, v10
	v_fmac_f32_e32 v7, v6, v6
	v_add_f32_e32 v0, v8, v1
	v_lshlrev_b32_e32 v11, 16, v5
	v_mul_f32_e32 v12, v12, v12
	v_fmac_f32_e32 v10, v9, v9
	v_add_f32_e32 v0, v0, v7
	v_add_f32_e32 v0, v0, v10
	v_fmac_f32_e32 v12, v11, v11
	v_add_f32_e32 v0, v0, v12
	v_mov_b32_e32 v1, v0
	s_nop 1
	v_permlane16_swap_b32_e32 v0, v1
	global_store_dwordx4 v[22:23], v[2:5], off offset:256
	s_waitcnt lgkmcnt(0)
	v_add_f32_e32 v0, v0, v1
	v_mov_b32_e32 v1, v0
	s_nop 1
	v_permlane32_swap_b32_e32 v0, v1
	s_and_saveexec_b64 s[44:45], s[40:41]
	s_cbranch_execz .LBB0_874
	v_lshlrev_b64 v[2:3], 6, v[16:17]
	v_lshl_add_u64 v[2:3], s[20:21], 0, v[2:3]
	v_lshl_add_u64 v[2:3], s[34:35], 2, v[2:3]
	s_lshl_b32 s36, s27, 2
	v_lshl_add_u64 v[2:3], v[2:3], 0, s[36:37]
	s_waitcnt lgkmcnt(0)
	v_add_f32_e32 v0, v0, v1
	global_store_dword v[2:3], v0, off
